# attention loops: next-tile LDS-DMA block issued after the K fragment ds_reads (in the LDS latency shadow) instead of before them; m0 wait states restored
# baseline (speedup 1.0000x reference)
; template <int DQK, bool MIXA, bool PIPE>
; DI void attn_item(const Params& P, int layer, char* smem, int b, int h, int qt) {
;     ...
;   auto issue_loads = [&](int kt) __attribute__((always_inline)) {
;     const char* kbp = (const char*)(Kp + (size_t)(kt * 64) * ldk);
;     const char* vbp = (const char*)(VT + kt * 64);
;     char* sk = smem + (kt & 1) * STG_B;
; #pragma unroll
;     for (int i = 0; i < NKI; ++i)
;       __builtin_amdgcn_global_load_lds((const unsigned*)(kbp + koff[i]), (unsigned*)(sk + (w * NKI + i) * 1024), 16, 0, 0);
; #pragma unroll
;     for (int i = 0; i < 2; ++i)
;       __builtin_amdgcn_global_load_lds((const unsigned*)(vbp + voff[i]), (unsigned*)(sk + KTILE_B + (w * 2 + i) * 1024), 16, 0, 0);
;     ...
;   for (int kt = 0; kt < nkt; ++kt) {
;     unsigned mw[2] = {mwn[0], mwn[1]};
;     if (kt + 1 < nkt) issue_loads(kt + 1);
;     const char* Ks = smem + (kt & 1) * STG_B;
;     const char* Vs = Ks + KTILE_B;
;     if (kt <= cw) {
;       const int kc = kt;
;       bf16x8 kf[2][NS];
; #pragma unroll
;       for (int kb = 0; kb < 2; ++kb)
; #pragma unroll
;         for (int s = 0; s < NS; ++s) kf[kb][s] = *(const bf16x8*)(Ks + (32 * kb + pr) * KROWB + (((2 * s + H) ^ swk) << 4));
;       __builtin_amdgcn_sched_barrier(0);
;       f32x16 sacc[2];
; #pragma unroll
;       for (int kb = 0; kb < 2; ++kb)
; #pragma unroll
;         for (int i = 0; i < 16; ++i) sacc[kb][i] = 0.f;
; #pragma unroll
;       for (int s = 0; s < NS; ++s) sacc[0] = __builtin_amdgcn_mfma_f32_32x32x16_bf16(kf[0][s], qf[s], sacc[0], 0, 0, 0);
.LBB0_87:
	s_add_i32 s20, s22, 1
	s_movk_i32 s21, 0x5000
	s_cmp_gt_i32 s22, s78
	s_cbranch_scc1 .LmlaE_skipdma
	ds_read_b128 v[32:35], v168
	ds_read_b128 v[36:39], v168 offset:6144
	ds_read_b128 v[40:43], v170
	ds_read_b128 v[148:151], v170 offset:6144
	ds_read_b128 v[44:47], v172
	ds_read_b128 v[152:155], v172 offset:6144
	ds_read_b128 v[88:91], v174
	ds_read_b128 v[156:159], v174 offset:6144
	ds_read_b128 v[92:95], v176
	ds_read_b128 v[208:211], v176 offset:6144
	ds_read_b128 v[96:99], v244
	ds_read_b128 v[212:215], v244 offset:6144
	s_add_u32 m0, s21, s32
	s_add_u32 s18, s21, s73
	global_load_lds_dwordx4 v120, s[36:37]
	s_add_u32 m0, m0, 0x400
	s_nop 0
	global_load_lds_dwordx4 v122, s[36:37]
	s_add_u32 m0, m0, 0x400
	s_nop 0
	global_load_lds_dwordx4 v124, s[36:37]
	s_add_u32 m0, s18, 0x3000
	s_nop 0
	global_load_lds_dwordx4 v116, s[38:39]
	s_add_u32 m0, s18, 0x3400
	s_nop 0
	global_load_lds_dwordx4 v118, s[38:39]
	s_waitcnt lgkmcnt(0)
	v_mfma_f32_32x32x16_bf16 v[48:63], v[32:35], v[84:87], v[228:243]
	ds_read_b128 v[216:219], v245 offset:12288
	ds_read_b128 v[108:111], v246 offset:12288
	v_mfma_f32_32x32x16_bf16 v[48:63], v[40:43], v[80:83], v[48:63]
	v_mfma_f32_32x32x16_bf16 v[48:63], v[44:47], v[76:79], v[48:63]
	v_mfma_f32_32x32x16_bf16 v[48:63], v[88:91], v[72:75], v[48:63]
	ds_read_b128 v[88:91], v247 offset:12288
	v_mfma_f32_32x32x16_bf16 v[48:63], v[92:95], v[68:71], v[48:63]
	v_mfma_f32_32x32x16_bf16 v[48:63], v[96:99], v[64:67], v[48:63]
	ds_read_b128 v[92:95], v248 offset:12288
	ds_read_b128 v[220:223], v245 offset:16384
	ds_read_b128 v[104:107], v246 offset:16384
	ds_read_b128 v[100:103], v247 offset:16384
	ds_read_b128 v[96:99], v248 offset:16384
	s_nop 6
	s_nop 0
	v_exp_f32_e32 v32, v62
	v_exp_f32_e32 v33, v63
	s_nop 0
	v_add_f32_e32 v224, 0, v32
	v_add_f32_e32 v225, 0, v33
	v_cvt_pk_bf16_f32 v63, v32, v33
	v_mfma_f32_32x32x16_bf16 v[32:47], v[36:39], v[84:87], v[228:243]
	v_mfma_f32_32x32x16_bf16 v[32:47], v[148:151], v[80:83], v[32:47]
	v_exp_f32_e32 v60, v60
	v_exp_f32_e32 v61, v61
	s_nop 0
	v_add_f32_e32 v224, v60, v224
	v_add_f32_e32 v225, v61, v225
	v_cvt_pk_bf16_f32 v62, v60, v61
	v_exp_f32_e32 v58, v58
	v_exp_f32_e32 v59, v59
	v_exp_f32_e32 v56, v56
	v_exp_f32_e32 v57, v57
	v_mfma_f32_32x32x16_bf16 v[32:47], v[152:155], v[76:79], v[32:47]
	v_add_f32_e64 v148, v58, v224
	v_add_f32_e64 v149, v59, v225
	v_cvt_pk_bf16_f32 v61, v58, v59
	v_add_f32_e64 v58, v56, v148
	v_add_f32_e64 v59, v57, v149
	v_cvt_pk_bf16_f32 v60, v56, v57
	v_mfma_f32_32x32x16_bf16 v[32:47], v[156:159], v[72:75], v[32:47]
	v_exp_f32_e32 v54, v54
	v_exp_f32_e32 v55, v55
	s_nop 0
	v_add_f32_e32 v56, v54, v58
	v_add_f32_e32 v57, v55, v59
	v_cvt_pk_bf16_f32 v55, v54, v55
	v_mfma_f32_32x32x16_bf16 v[32:47], v[208:211], v[68:71], v[32:47]
	v_exp_f32_e32 v52, v52
	v_exp_f32_e32 v53, v53
	s_nop 0
	v_add_f32_e32 v56, v52, v56
	v_add_f32_e32 v57, v53, v57
	v_cvt_pk_bf16_f32 v54, v52, v53
	v_exp_f32_e32 v50, v50
	v_exp_f32_e32 v51, v51
	v_exp_f32_e32 v48, v48
	v_exp_f32_e32 v49, v49
	v_mfma_f32_32x32x16_bf16 v[32:47], v[212:215], v[64:67], v[32:47]
	v_add_f32_e64 v56, v50, v56
	v_add_f32_e64 v57, v51, v57
	v_cvt_pk_bf16_f32 v53, v50, v51
	v_cvt_pk_bf16_f32 v52, v48, v49
	v_add_f32_e64 v48, v48, v56
	v_add_f32_e64 v49, v49, v57
	s_waitcnt lgkmcnt(0)
	v_mfma_f32_32x32x16_bf16 v[0:15], v[216:219], v[52:55], v[0:15]
	s_nop 3
	v_exp_f32_e32 v46, v46
	v_exp_f32_e32 v47, v47
	v_exp_f32_e32 v44, v44
	v_exp_f32_e32 v45, v45
	v_add_f32_e32 v48, v48, v46
	v_add_f32_e32 v49, v49, v47
	v_cvt_pk_bf16_f32 v47, v46, v47
	v_add_f32_e32 v48, v44, v48
	v_add_f32_e32 v49, v45, v49
	v_cvt_pk_bf16_f32 v46, v44, v45
	v_mfma_f32_32x32x16_bf16 v[16:31], v[220:223], v[52:55], v[16:31]
	v_exp_f32_e32 v42, v42
	v_exp_f32_e32 v43, v43
	v_exp_f32_e32 v40, v40
	v_exp_f32_e32 v41, v41
	v_add_f32_e32 v48, v42, v48
	v_add_f32_e32 v49, v43, v49
	v_cvt_pk_bf16_f32 v45, v42, v43
	v_add_f32_e32 v42, v40, v48
	v_add_f32_e32 v43, v41, v49
	v_cvt_pk_bf16_f32 v44, v40, v41
	v_mfma_f32_32x32x16_bf16 v[0:15], v[108:111], v[60:63], v[0:15]
	v_exp_f32_e32 v38, v38
	v_exp_f32_e32 v39, v39
	v_exp_f32_e32 v36, v36
	v_exp_f32_e32 v37, v37
	v_add_f32_e32 v40, v38, v42
	v_add_f32_e32 v41, v39, v43
	v_cvt_pk_bf16_f32 v39, v38, v39
	v_add_f32_e32 v40, v36, v40
	v_add_f32_e32 v41, v37, v41
	v_cvt_pk_bf16_f32 v38, v36, v37
	v_mfma_f32_32x32x16_bf16 v[16:31], v[104:107], v[60:63], v[16:31]
	v_exp_f32_e32 v34, v34
	v_exp_f32_e32 v35, v35
	v_exp_f32_e32 v32, v32
	v_exp_f32_e32 v33, v33
	v_cvt_pk_bf16_f32 v37, v34, v35
	v_cvt_pk_bf16_f32 v36, v32, v33
	s_nop 1
	v_mfma_f32_32x32x16_bf16 v[0:15], v[88:91], v[36:39], v[0:15]
	v_add_f32_e64 v34, v34, v40
	v_add_f32_e64 v35, v35, v41
	v_add_f32_e64 v32, v32, v34
	v_add_f32_e64 v33, v33, v35
	v_add_f32_e32 v32, v32, v33
	v_add_f32_e32 v126, v126, v32
	v_mfma_f32_32x32x16_bf16 v[16:31], v[100:103], v[36:39], v[16:31]
	v_mfma_f32_32x32x16_bf16 v[0:15], v[92:95], v[44:47], v[0:15]
	v_mfma_f32_32x32x16_bf16 v[16:31], v[96:99], v[44:47], v[16:31]
	s_branch .Lmla_o86

; template <int DQK, bool MIXA, bool PIPE>
; DI void attn_item(const Params& P, int layer, char* smem, int b, int h, int qt) {
;     ...
;   auto issue_loads = [&](int kt) __attribute__((always_inline)) {
;     const char* kbp = (const char*)(Kp + (size_t)(kt * 64) * ldk);
;     const char* vbp = (const char*)(VT + kt * 64);
;     char* sk = smem + (kt & 1) * STG_B;
; #pragma unroll
;     for (int i = 0; i < NKI; ++i)
;       __builtin_amdgcn_global_load_lds((const unsigned*)(kbp + koff[i]), (unsigned*)(sk + (w * NKI + i) * 1024), 16, 0, 0);
; #pragma unroll
;     for (int i = 0; i < 2; ++i)
;       __builtin_amdgcn_global_load_lds((const unsigned*)(vbp + voff[i]), (unsigned*)(sk + KTILE_B + (w * 2 + i) * 1024), 16, 0, 0);
;     ...
;   for (int kt = 0; kt < nkt; ++kt) {
;     unsigned mw[2] = {mwn[0], mwn[1]};
;     if (kt + 1 < nkt) issue_loads(kt + 1);
;     const char* Ks = smem + (kt & 1) * STG_B;
;     const char* Vs = Ks + KTILE_B;
;     if (kt <= cw) {
;       const int kc = kt;
;       bf16x8 kf[2][NS];
; #pragma unroll
;       for (int kb = 0; kb < 2; ++kb)
; #pragma unroll
;         for (int s = 0; s < NS; ++s) kf[kb][s] = *(const bf16x8*)(Ks + (32 * kb + pr) * KROWB + (((2 * s + H) ^ swk) << 4));
;       __builtin_amdgcn_sched_barrier(0);
;       f32x16 sacc[2];
; #pragma unroll
;       for (int kb = 0; kb < 2; ++kb)
; #pragma unroll
;         for (int i = 0; i < 16; ++i) sacc[kb][i] = 0.f;
; #pragma unroll
;       for (int s = 0; s < NS; ++s) sacc[0] = __builtin_amdgcn_mfma_f32_32x32x16_bf16(kf[0][s], qf[s], sacc[0], 0, 0, 0);
.Lmla_o87:
	s_add_i32 s20, s22, 1
	s_mov_b32 s21, 0
	s_cmp_gt_i32 s22, s78
	s_cbranch_scc1 .LmlaO_skipdma
	ds_read_b128 v[32:35], v168 offset:20480
	ds_read_b128 v[36:39], v168 offset:26624
	ds_read_b128 v[40:43], v170 offset:20480
	ds_read_b128 v[148:151], v170 offset:26624
	ds_read_b128 v[44:47], v172 offset:20480
	ds_read_b128 v[152:155], v172 offset:26624
	ds_read_b128 v[88:91], v174 offset:20480
	ds_read_b128 v[156:159], v174 offset:26624
	ds_read_b128 v[92:95], v176 offset:20480
	ds_read_b128 v[208:211], v176 offset:26624
	ds_read_b128 v[96:99], v244 offset:20480
	ds_read_b128 v[212:215], v244 offset:26624
	s_add_u32 m0, s21, s32
	s_add_u32 s18, s21, s73
	global_load_lds_dwordx4 v120, s[36:37]
	s_add_u32 m0, m0, 0x400
	s_nop 0
	global_load_lds_dwordx4 v122, s[36:37]
	s_add_u32 m0, m0, 0x400
	s_nop 0
	global_load_lds_dwordx4 v124, s[36:37]
	s_add_u32 m0, s18, 0x3000
	s_nop 0
	global_load_lds_dwordx4 v116, s[38:39]
	s_add_u32 m0, s18, 0x3400
	s_nop 0
	global_load_lds_dwordx4 v118, s[38:39]
	s_waitcnt lgkmcnt(0)
	v_mfma_f32_32x32x16_bf16 v[48:63], v[32:35], v[84:87], v[228:243]
	ds_read_b128 v[216:219], v245 offset:32768
	ds_read_b128 v[108:111], v246 offset:32768
	v_mfma_f32_32x32x16_bf16 v[48:63], v[40:43], v[80:83], v[48:63]
	v_mfma_f32_32x32x16_bf16 v[48:63], v[44:47], v[76:79], v[48:63]
	v_mfma_f32_32x32x16_bf16 v[48:63], v[88:91], v[72:75], v[48:63]
	ds_read_b128 v[88:91], v247 offset:32768
	v_mfma_f32_32x32x16_bf16 v[48:63], v[92:95], v[68:71], v[48:63]
	v_mfma_f32_32x32x16_bf16 v[48:63], v[96:99], v[64:67], v[48:63]
	ds_read_b128 v[92:95], v248 offset:32768
	ds_read_b128 v[220:223], v245 offset:36864
	ds_read_b128 v[104:107], v246 offset:36864
	ds_read_b128 v[100:103], v247 offset:36864
	ds_read_b128 v[96:99], v248 offset:36864
	s_nop 6
	s_nop 0
	v_exp_f32_e32 v32, v62
	v_exp_f32_e32 v33, v63
	s_nop 0
	v_add_f32_e32 v224, 0, v32
	v_add_f32_e32 v225, 0, v33
	v_cvt_pk_bf16_f32 v63, v32, v33
	v_mfma_f32_32x32x16_bf16 v[32:47], v[36:39], v[84:87], v[228:243]
	v_mfma_f32_32x32x16_bf16 v[32:47], v[148:151], v[80:83], v[32:47]
	v_exp_f32_e32 v60, v60
	v_exp_f32_e32 v61, v61
	s_nop 0
	v_add_f32_e32 v224, v60, v224
	v_add_f32_e32 v225, v61, v225
	v_cvt_pk_bf16_f32 v62, v60, v61
	v_exp_f32_e32 v58, v58
	v_exp_f32_e32 v59, v59
	v_exp_f32_e32 v56, v56
	v_exp_f32_e32 v57, v57
	v_mfma_f32_32x32x16_bf16 v[32:47], v[152:155], v[76:79], v[32:47]
	v_add_f32_e64 v148, v58, v224
	v_add_f32_e64 v149, v59, v225
	v_cvt_pk_bf16_f32 v61, v58, v59
	v_add_f32_e64 v58, v56, v148
	v_add_f32_e64 v59, v57, v149
	v_cvt_pk_bf16_f32 v60, v56, v57
	v_mfma_f32_32x32x16_bf16 v[32:47], v[156:159], v[72:75], v[32:47]
	v_exp_f32_e32 v54, v54
	v_exp_f32_e32 v55, v55
	s_nop 0
	v_add_f32_e32 v56, v54, v58
	v_add_f32_e32 v57, v55, v59
	v_cvt_pk_bf16_f32 v55, v54, v55
	v_mfma_f32_32x32x16_bf16 v[32:47], v[208:211], v[68:71], v[32:47]
	v_exp_f32_e32 v52, v52
	v_exp_f32_e32 v53, v53
	s_nop 0
	v_add_f32_e32 v56, v52, v56
	v_add_f32_e32 v57, v53, v57
	v_cvt_pk_bf16_f32 v54, v52, v53
	v_exp_f32_e32 v50, v50
	v_exp_f32_e32 v51, v51
	v_exp_f32_e32 v48, v48
	v_exp_f32_e32 v49, v49
	v_mfma_f32_32x32x16_bf16 v[32:47], v[212:215], v[64:67], v[32:47]
	v_add_f32_e64 v56, v50, v56
	v_add_f32_e64 v57, v51, v57
	v_cvt_pk_bf16_f32 v53, v50, v51
	v_cvt_pk_bf16_f32 v52, v48, v49
	v_add_f32_e64 v48, v48, v56
	v_add_f32_e64 v49, v49, v57
	s_waitcnt lgkmcnt(0)
	v_mfma_f32_32x32x16_bf16 v[0:15], v[216:219], v[52:55], v[0:15]
	s_nop 3
	v_exp_f32_e32 v46, v46
	v_exp_f32_e32 v47, v47
	v_exp_f32_e32 v44, v44
	v_exp_f32_e32 v45, v45
	v_add_f32_e32 v48, v48, v46
	v_add_f32_e32 v49, v49, v47
	v_cvt_pk_bf16_f32 v47, v46, v47
	v_add_f32_e32 v48, v44, v48
	v_add_f32_e32 v49, v45, v49
	v_cvt_pk_bf16_f32 v46, v44, v45
	v_mfma_f32_32x32x16_bf16 v[16:31], v[220:223], v[52:55], v[16:31]
	v_exp_f32_e32 v42, v42
	v_exp_f32_e32 v43, v43
	v_exp_f32_e32 v40, v40
	v_exp_f32_e32 v41, v41
	v_add_f32_e32 v48, v42, v48
	v_add_f32_e32 v49, v43, v49
	v_cvt_pk_bf16_f32 v45, v42, v43
	v_add_f32_e32 v42, v40, v48
	v_add_f32_e32 v43, v41, v49
	v_cvt_pk_bf16_f32 v44, v40, v41
	v_mfma_f32_32x32x16_bf16 v[0:15], v[108:111], v[60:63], v[0:15]
	v_exp_f32_e32 v38, v38
	v_exp_f32_e32 v39, v39
	v_exp_f32_e32 v36, v36
	v_exp_f32_e32 v37, v37
	v_add_f32_e32 v40, v38, v42
	v_add_f32_e32 v41, v39, v43
	v_cvt_pk_bf16_f32 v39, v38, v39
	v_add_f32_e32 v40, v36, v40
	v_add_f32_e32 v41, v37, v41
	v_cvt_pk_bf16_f32 v38, v36, v37
	v_mfma_f32_32x32x16_bf16 v[16:31], v[104:107], v[60:63], v[16:31]
	v_exp_f32_e32 v34, v34
	v_exp_f32_e32 v35, v35
	v_exp_f32_e32 v32, v32
	v_exp_f32_e32 v33, v33
	v_cvt_pk_bf16_f32 v37, v34, v35
	v_cvt_pk_bf16_f32 v36, v32, v33
	s_nop 1
	v_mfma_f32_32x32x16_bf16 v[0:15], v[88:91], v[36:39], v[0:15]
	v_add_f32_e64 v34, v34, v40
	v_add_f32_e64 v35, v35, v41
	v_add_f32_e64 v32, v32, v34
	v_add_f32_e64 v33, v33, v35
	v_add_f32_e32 v32, v32, v33
	v_add_f32_e32 v126, v126, v32
	v_mfma_f32_32x32x16_bf16 v[16:31], v[100:103], v[36:39], v[16:31]
	v_mfma_f32_32x32x16_bf16 v[0:15], v[92:95], v[44:47], v[0:15]
	v_mfma_f32_32x32x16_bf16 v[16:31], v[96:99], v[44:47], v[16:31]
	s_branch .LBB0_86
.LmlaE_skipdma:
	s_add_u32 m0, s21, s32
	s_add_u32 s18, s21, s73
	global_load_lds_dwordx4 v120, s[36:37]
	s_add_u32 m0, m0, 0x400
	s_nop 0
	global_load_lds_dwordx4 v122, s[36:37]
	s_add_u32 m0, m0, 0x400
	s_nop 0
	global_load_lds_dwordx4 v124, s[36:37]
	s_add_u32 m0, s18, 0x3000
	s_nop 0
	global_load_lds_dwordx4 v116, s[38:39]
	s_add_u32 m0, s18, 0x3400
	s_nop 0
	global_load_lds_dwordx4 v118, s[38:39]
	s_branch .Lmla_o86

; template <int DQK, bool MIXA, bool PIPE>
; DI void attn_item(const Params& P, int layer, char* smem, int b, int h, int qt) {
;     ...
;   auto issue_loads = [&](int kt) __attribute__((always_inline)) {
;     const char* kbp = (const char*)(Kp + (size_t)(kt * 64) * ldk);
;     const char* vbp = (const char*)(VT + kt * 64);
;     char* sk = smem + (kt & 1) * STG_B;
; #pragma unroll
;     for (int i = 0; i < NKI; ++i)
;       __builtin_amdgcn_global_load_lds((const unsigned*)(kbp + koff[i]), (unsigned*)(sk + (w * NKI + i) * 1024), 16, 0, 0);
; #pragma unroll
;     for (int i = 0; i < 2; ++i)
;       __builtin_amdgcn_global_load_lds((const unsigned*)(vbp + voff[i]), (unsigned*)(sk + KTILE_B + (w * 2 + i) * 1024), 16, 0, 0);
;     if (MIXA) {
;       if (kt <= cw) {
;         const unsigned* mp = mask + mask_base(b, cw) + (2 * kt) * 64 + (qpos & 63);
;         mwn[0] = mp[0]; mwn[1] = mp[64];
;       }
;     }
;   };
;   issue_loads(0);
;   f32x16 o[2];
; #pragma unroll
;   for (int d = 0; d < 2; ++d)
; #pragma unroll
;     for (int i = 0; i < 16; ++i) o[d][i] = 0.f;
;   float l = 0.f;
;   const int pr = (l31 & ~12) | ((l31 & 4) << 1) | ((l31 & 8) >> 1);
;   const int swk = MIXA ? ((pr >> 1) & 7) : ((pr >> 2) & 3), swv = (l31 >> 1) & 7;
;   asm volatile("s_waitcnt vmcnt(0)" ::: "memory");
;   __syncthreads();
;   for (int kt = 0; kt < nkt; ++kt) {
;     unsigned mw[2] = {mwn[0], mwn[1]};
;     if (kt + 1 < nkt) issue_loads(kt + 1);
;     const char* Ks = smem + (kt & 1) * STG_B;
;     const char* Vs = Ks + KTILE_B;
;     if (kt <= cw) {
;       const int kc = kt;
;       bf16x8 kf[2][NS];
; #pragma unroll
;       for (int kb = 0; kb < 2; ++kb)
; #pragma unroll
;         for (int s = 0; s < NS; ++s) kf[kb][s] = *(const bf16x8*)(Ks + (32 * kb + pr) * KROWB + (((2 * s + H) ^ swk) << 4));
;       __builtin_amdgcn_sched_barrier(0);
;       f32x16 sacc[2];
; #pragma unroll
;       for (int kb = 0; kb < 2; ++kb)
; #pragma unroll
;         for (int i = 0; i < 16; ++i) sacc[kb][i] = 0.f;
; #pragma unroll
;       for (int s = 0; s < NS; ++s) sacc[0] = __builtin_amdgcn_mfma_f32_32x32x16_bf16(kf[0][s], qf[s], sacc[0], 0, 0, 0);
;       bf16x8 vf[2][2][2];
; #pragma unroll
;       for (int d = 0; d < 2; ++d)
; #pragma unroll
;         for (int kb = 0; kb < 2; ++kb)
; #pragma unroll
;           for (int s2 = 0; s2 < 2; ++s2)
.LBB0_110:
	s_add_i32 s20, s22, 1
	s_movk_i32 s21, 0x5000
	s_cmp_gt_i32 s22, s78
	s_cbranch_scc1 .LmixE_skipdma
	ds_read_b128 v[36:39], v168
	ds_read_b128 v[32:35], v168 offset:4096
	ds_read_b128 v[40:43], v170
	ds_read_b128 v[120:123], v170 offset:4096
	ds_read_b128 v[44:47], v172
	ds_read_b128 v[116:119], v172 offset:4096
	ds_read_b128 v[80:83], v174
	ds_read_b128 v[108:111], v174 offset:4096
	s_add_u32 m0, s21, s32
	s_nop 0
	global_load_lds_dwordx4 v140, s[36:37]
	s_add_u32 m0, m0, 0x400
	s_nop 0
	global_load_lds_dwordx4 v142, s[36:37]
	s_add_u32 m0, m0, 0x1c00
	s_nop 0
	global_load_lds_dwordx4 v132, s[38:39]
	s_add_u32 m0, m0, 0x400
	s_nop 0
	global_load_lds_dwordx4 v134, s[38:39]
	s_cmp_lt_i32 s22, s78
	s_cselect_b64 s[42:43], exec, 0
	s_cbranch_scc0 .LmixE_m112
	global_load_dword v156, v130, s[76:77] offset:512
	global_load_dword v136, v130, s[76:77] offset:768
.LmixE_m112:
	s_waitcnt lgkmcnt(0)
	v_mfma_f32_32x32x16_bf16 v[48:63], v[36:39], v[76:79], v[228:243]
	ds_read_b128 v[112:115], v245 offset:8192
	ds_read_b128 v[100:103], v246 offset:8192
	v_mfma_f32_32x32x16_bf16 v[48:63], v[40:43], v[72:75], v[48:63]
	v_mfma_f32_32x32x16_bf16 v[48:63], v[44:47], v[68:71], v[48:63]
	v_mfma_f32_32x32x16_bf16 v[48:63], v[80:83], v[64:67], v[48:63]
	ds_read_b128 v[80:83], v247 offset:8192
	ds_read_b128 v[84:87], v248 offset:8192
	ds_read_b128 v[104:107], v245 offset:12288
	ds_read_b128 v[96:99], v246 offset:12288
	ds_read_b128 v[92:95], v247 offset:12288
	ds_read_b128 v[88:91], v248 offset:12288
	s_nop 4
	s_cmp_ge_i32 s22, s93
	s_cbranch_scc1 .Lmixa_near_0

; template <int DQK, bool MIXA, bool PIPE>
; DI void attn_item(const Params& P, int layer, char* smem, int b, int h, int qt) {
;     ...
;   auto issue_loads = [&](int kt) __attribute__((always_inline)) {
;     const char* kbp = (const char*)(Kp + (size_t)(kt * 64) * ldk);
;     const char* vbp = (const char*)(VT + kt * 64);
;     char* sk = smem + (kt & 1) * STG_B;
; #pragma unroll
;     for (int i = 0; i < NKI; ++i)
;       __builtin_amdgcn_global_load_lds((const unsigned*)(kbp + koff[i]), (unsigned*)(sk + (w * NKI + i) * 1024), 16, 0, 0);
; #pragma unroll
;     for (int i = 0; i < 2; ++i)
;       __builtin_amdgcn_global_load_lds((const unsigned*)(vbp + voff[i]), (unsigned*)(sk + KTILE_B + (w * 2 + i) * 1024), 16, 0, 0);
;     if (MIXA) {
;       if (kt <= cw) {
;         const unsigned* mp = mask + mask_base(b, cw) + (2 * kt) * 64 + (qpos & 63);
;         mwn[0] = mp[0]; mwn[1] = mp[64];
;       }
;     }
;   };
;   issue_loads(0);
;   f32x16 o[2];
; #pragma unroll
;   for (int d = 0; d < 2; ++d)
; #pragma unroll
;     for (int i = 0; i < 16; ++i) o[d][i] = 0.f;
;   float l = 0.f;
;   const int pr = (l31 & ~12) | ((l31 & 4) << 1) | ((l31 & 8) >> 1);
;   const int swk = MIXA ? ((pr >> 1) & 7) : ((pr >> 2) & 3), swv = (l31 >> 1) & 7;
;   asm volatile("s_waitcnt vmcnt(0)" ::: "memory");
;   __syncthreads();
;   for (int kt = 0; kt < nkt; ++kt) {
;     unsigned mw[2] = {mwn[0], mwn[1]};
;     if (kt + 1 < nkt) issue_loads(kt + 1);
;     const char* Ks = smem + (kt & 1) * STG_B;
;     const char* Vs = Ks + KTILE_B;
;     if (kt <= cw) {
;       const int kc = kt;
;       bf16x8 kf[2][NS];
; #pragma unroll
;       for (int kb = 0; kb < 2; ++kb)
; #pragma unroll
;         for (int s = 0; s < NS; ++s) kf[kb][s] = *(const bf16x8*)(Ks + (32 * kb + pr) * KROWB + (((2 * s + H) ^ swk) << 4));
;       __builtin_amdgcn_sched_barrier(0);
;       f32x16 sacc[2];
; #pragma unroll
;       for (int kb = 0; kb < 2; ++kb)
; #pragma unroll
;         for (int i = 0; i < 16; ++i) sacc[kb][i] = 0.f;
; #pragma unroll
;       for (int s = 0; s < NS; ++s) sacc[0] = __builtin_amdgcn_mfma_f32_32x32x16_bf16(kf[0][s], qf[s], sacc[0], 0, 0, 0);
;       bf16x8 vf[2][2][2];
; #pragma unroll
;       for (int d = 0; d < 2; ++d)
; #pragma unroll
;         for (int kb = 0; kb < 2; ++kb)
; #pragma unroll
;           for (int s2 = 0; s2 < 2; ++s2)
.Lmixa_o_o110:
	s_add_i32 s20, s22, 1
	s_mov_b32 s21, 0
	s_cmp_gt_i32 s22, s78
	s_cbranch_scc1 .LmixO_skipdma
	ds_read_b128 v[36:39], v168 offset:20480
	ds_read_b128 v[32:35], v168 offset:24576
	ds_read_b128 v[40:43], v170 offset:20480
	ds_read_b128 v[120:123], v170 offset:24576
	ds_read_b128 v[44:47], v172 offset:20480
	ds_read_b128 v[116:119], v172 offset:24576
	ds_read_b128 v[80:83], v174 offset:20480
	ds_read_b128 v[108:111], v174 offset:24576
	s_add_u32 m0, s21, s32
	s_nop 0
	global_load_lds_dwordx4 v140, s[36:37]
	s_add_u32 m0, m0, 0x400
	s_nop 0
	global_load_lds_dwordx4 v142, s[36:37]
	s_add_u32 m0, m0, 0x1c00
	s_nop 0
	global_load_lds_dwordx4 v132, s[38:39]
	s_add_u32 m0, m0, 0x400
	s_nop 0
	global_load_lds_dwordx4 v134, s[38:39]
	s_cmp_lt_i32 s22, s78
	s_cselect_b64 s[42:43], exec, 0
	s_cbranch_scc0 .LmixO_m112
	global_load_dword v156, v130, s[76:77] offset:512
	global_load_dword v136, v130, s[76:77] offset:768
.LmixO_m112:
	s_waitcnt lgkmcnt(0)
	v_mfma_f32_32x32x16_bf16 v[48:63], v[36:39], v[76:79], v[228:243]
	ds_read_b128 v[112:115], v245 offset:28672
	ds_read_b128 v[100:103], v246 offset:28672
	v_mfma_f32_32x32x16_bf16 v[48:63], v[40:43], v[72:75], v[48:63]
	v_mfma_f32_32x32x16_bf16 v[48:63], v[44:47], v[68:71], v[48:63]
	v_mfma_f32_32x32x16_bf16 v[48:63], v[80:83], v[64:67], v[48:63]
	ds_read_b128 v[80:83], v247 offset:28672
	ds_read_b128 v[84:87], v248 offset:28672
	ds_read_b128 v[104:107], v245 offset:32768
	ds_read_b128 v[96:99], v246 offset:32768
	ds_read_b128 v[92:95], v247 offset:32768
	ds_read_b128 v[88:91], v248 offset:32768
	s_nop 4
	s_cmp_ge_i32 s22, s93
	s_cbranch_scc1 .Lmixa_o_near_0

; template <int DQK, bool MIXA, bool PIPE>
; DI void attn_item(const Params& P, int layer, char* smem, int b, int h, int qt) {
;     ...
;   auto issue_loads = [&](int kt) __attribute__((always_inline)) {
;     const char* kbp = (const char*)(Kp + (size_t)(kt * 64) * ldk);
;     const char* vbp = (const char*)(VT + kt * 64);
;     char* sk = smem + (kt & 1) * STG_B;
; #pragma unroll
;     for (int i = 0; i < NKI; ++i)
;       __builtin_amdgcn_global_load_lds((const unsigned*)(kbp + koff[i]), (unsigned*)(sk + (w * NKI + i) * 1024), 16, 0, 0);
; #pragma unroll
;     for (int i = 0; i < 2; ++i)
;       __builtin_amdgcn_global_load_lds((const unsigned*)(vbp + voff[i]), (unsigned*)(sk + KTILE_B + (w * 2 + i) * 1024), 16, 0, 0);
;     if (MIXA) {
;       if (kt <= cw) {
;         const unsigned* mp = mask + mask_base(b, cw) + (2 * kt) * 64 + (qpos & 63);
;         mwn[0] = mp[0]; mwn[1] = mp[64];
;       }
;     }
.LmixE_skipdma:
	s_add_u32 m0, s21, s32
	s_nop 0
	global_load_lds_dwordx4 v140, s[36:37]
	s_add_u32 m0, m0, 0x400
	s_nop 0
	global_load_lds_dwordx4 v142, s[36:37]
	s_add_u32 m0, m0, 0x1c00
	s_nop 0
	global_load_lds_dwordx4 v132, s[38:39]
	s_add_u32 m0, m0, 0x400
	s_nop 0
	global_load_lds_dwordx4 v134, s[38:39]
	s_cmp_lt_i32 s22, s78
	s_cselect_b64 s[42:43], exec, 0
	s_cbranch_scc0 .LmixE_s112
	global_load_dword v156, v130, s[76:77] offset:512
	global_load_dword v136, v130, s[76:77] offset:768
.LmixE_s112:
	s_branch .Lmixa_o_o109
